# RMS-norm + modulation of the latent rows fused behind the residual GEMM epilogues: h stays in the accumulators, row sums exchanged between the four workgroups of a tile row, the norm phases only handl
# speedup vs baseline: 1.0059x; 1.0059x over previous
.LBB0_163:
	s_mov_b32 s44, s84
	s_and_b64 vcc, exec, s[38:39]
	s_mov_b32 s45, s19
	s_mov_b32 s87, s83
	s_mov_b32 s86, s85
	s_mov_b64 s[42:43], s[40:41]
	s_mov_b64 s[34:35], s[0:1]
	s_cbranch_vccnz .LBB0_191

.LBB0_182:
	s_add_i32 s91, s2, 2
	s_add_u32 s12, s34, 0x80
	s_addc_u32 s3, s35, 0
	s_add_i32 s13, 0, 0x10000
	v_add_u32_e32 v142, s13, v183
	ds_read_b128 v[130:133], v142
	ds_read_b128 v[134:137], v142 offset:1024
	ds_read_b128 v[138:141], v142 offset:2048
	ds_read_b128 v[142:145], v142 offset:3072
	s_cmp_eq_u32 s88, s2
	s_cselect_b32 s2, s0, s12
	s_cselect_b32 s3, s1, s3
	s_cselect_b32 s43, s41, s90
	s_cselect_b32 s42, s40, s89
	v_lshl_add_u64 v[190:191], s[34:35], 0, v[174:175]
	s_add_i32 m0, s55, 0xc000
	ds_read_b128 v[146:149], v184
	ds_read_b128 v[150:153], v184 offset:1024
	ds_read_b128 v[154:157], v184 offset:2048
	ds_read_b128 v[158:161], v184 offset:3072
	ds_read_b128 v[162:165], v184 offset:4096
	ds_read_b128 v[166:169], v184 offset:5120
	ds_read_b128 v[178:181], v184 offset:6144
	ds_read_b128 v[186:189], v184 offset:7168
	global_load_lds_dwordx4 v[190:191], off
	v_lshl_add_u64 v[190:191], s[34:35], 0, v[176:177]
	s_add_i32 m0, s55, 0xe000
	s_nop 0
	global_load_lds_dwordx4 v[190:191], off
	s_waitcnt lgkmcnt(8)
	s_barrier
	s_waitcnt lgkmcnt(0)
	s_waitcnt lgkmcnt(0)
	v_mfma_f32_16x16x32_bf16 v[126:129], v[130:133], v[146:149], v[126:129]
	v_mfma_f32_16x16x32_bf16 v[122:125], v[138:141], v[146:149], v[122:125]
	v_mfma_f32_16x16x32_bf16 v[118:121], v[130:133], v[154:157], v[118:121]
	v_mfma_f32_16x16x32_bf16 v[114:117], v[138:141], v[154:157], v[114:117]
	v_mfma_f32_16x16x32_bf16 v[110:113], v[130:133], v[162:165], v[110:113]
	v_mfma_f32_16x16x32_bf16 v[106:109], v[138:141], v[162:165], v[106:109]
	v_mfma_f32_16x16x32_bf16 v[102:105], v[130:133], v[178:181], v[102:105]
	v_mfma_f32_16x16x32_bf16 v[98:101], v[138:141], v[178:181], v[98:101]
	v_mfma_f32_16x16x32_bf16 v[126:129], v[134:137], v[150:153], v[126:129]
	v_mfma_f32_16x16x32_bf16 v[122:125], v[142:145], v[150:153], v[122:125]
	v_mfma_f32_16x16x32_bf16 v[118:121], v[134:137], v[158:161], v[118:121]
	v_mfma_f32_16x16x32_bf16 v[114:117], v[142:145], v[158:161], v[114:117]
	v_mfma_f32_16x16x32_bf16 v[110:113], v[134:137], v[166:169], v[110:113]
	v_mfma_f32_16x16x32_bf16 v[106:109], v[142:145], v[166:169], v[106:109]
	v_mfma_f32_16x16x32_bf16 v[102:105], v[134:137], v[186:189], v[102:105]
	v_mfma_f32_16x16x32_bf16 v[98:101], v[142:145], v[186:189], v[98:101]
	s_barrier
	s_add_i32 s92, 0, 0x14000
	s_add_i32 s12, s13, s54
	v_add_u32_e32 v185, s92, v183
	v_lshl_add_u64 v[230:231], s[42:43], 0, v[170:171]
	s_mov_b32 m0, s12
	ds_read_b128 v[190:193], v185
	ds_read_b128 v[194:197], v185 offset:1024
	ds_read_b128 v[198:201], v185 offset:2048
	ds_read_b128 v[226:229], v185 offset:3072
	global_load_lds_dwordx4 v[230:231], off
	v_lshl_add_u64 v[232:233], s[42:43], 0, v[172:173]
	s_add_i32 m0, s12, 0x2000
	s_nop 0
	global_load_lds_dwordx4 v[232:233], off
	s_barrier
	s_waitcnt lgkmcnt(0)
	s_waitcnt lgkmcnt(0)
	v_mfma_f32_16x16x32_bf16 v[62:65], v[190:193], v[146:149], v[62:65]
	v_mfma_f32_16x16x32_bf16 v[58:61], v[198:201], v[146:149], v[58:61]
	v_mfma_f32_16x16x32_bf16 v[54:57], v[190:193], v[154:157], v[54:57]
	v_mfma_f32_16x16x32_bf16 v[50:53], v[198:201], v[154:157], v[50:53]
	v_mfma_f32_16x16x32_bf16 v[46:49], v[190:193], v[162:165], v[46:49]
	v_mfma_f32_16x16x32_bf16 v[42:45], v[198:201], v[162:165], v[42:45]
	v_mfma_f32_16x16x32_bf16 v[38:41], v[190:193], v[178:181], v[38:41]
	v_mfma_f32_16x16x32_bf16 v[34:37], v[198:201], v[178:181], v[34:37]
	v_mfma_f32_16x16x32_bf16 v[62:65], v[194:197], v[150:153], v[62:65]
	v_mfma_f32_16x16x32_bf16 v[58:61], v[226:229], v[150:153], v[58:61]
	v_mfma_f32_16x16x32_bf16 v[54:57], v[194:197], v[158:161], v[54:57]
	v_mfma_f32_16x16x32_bf16 v[50:53], v[226:229], v[158:161], v[50:53]
	v_mfma_f32_16x16x32_bf16 v[46:49], v[194:197], v[166:169], v[46:49]
	v_mfma_f32_16x16x32_bf16 v[42:45], v[226:229], v[166:169], v[42:45]
	v_mfma_f32_16x16x32_bf16 v[38:41], v[194:197], v[186:189], v[38:41]
	v_mfma_f32_16x16x32_bf16 v[34:37], v[226:229], v[186:189], v[34:37]
	s_mov_b32 m0, s55
	v_lshl_add_u64 v[234:235], s[2:3], 0, v[170:171]
	s_barrier
	ds_read_b128 v[146:149], v184 offset:16384
	ds_read_b128 v[150:153], v184 offset:17408
	ds_read_b128 v[154:157], v184 offset:18432
	ds_read_b128 v[158:161], v184 offset:19456
	ds_read_b128 v[162:165], v184 offset:20480
	ds_read_b128 v[166:169], v184 offset:21504
	ds_read_b128 v[178:181], v184 offset:22528
	ds_read_b128 v[186:189], v184 offset:23552
	global_load_lds_dwordx4 v[234:235], off
	v_lshl_add_u64 v[236:237], s[2:3], 0, v[172:173]
	s_mov_b32 m0, s58
	s_nop 0
	global_load_lds_dwordx4 v[236:237], off
	s_barrier
	s_waitcnt lgkmcnt(0)
	s_waitcnt lgkmcnt(0)
	v_mfma_f32_16x16x32_bf16 v[94:97], v[130:133], v[146:149], v[94:97]
	v_mfma_f32_16x16x32_bf16 v[90:93], v[138:141], v[146:149], v[90:93]
	v_mfma_f32_16x16x32_bf16 v[86:89], v[130:133], v[154:157], v[86:89]
	v_mfma_f32_16x16x32_bf16 v[82:85], v[138:141], v[154:157], v[82:85]
	v_mfma_f32_16x16x32_bf16 v[78:81], v[130:133], v[162:165], v[78:81]
	v_mfma_f32_16x16x32_bf16 v[74:77], v[138:141], v[162:165], v[74:77]
	v_mfma_f32_16x16x32_bf16 v[70:73], v[130:133], v[178:181], v[70:73]
	v_mfma_f32_16x16x32_bf16 v[66:69], v[138:141], v[178:181], v[66:69]
	v_mfma_f32_16x16x32_bf16 v[94:97], v[134:137], v[150:153], v[94:97]
	v_mfma_f32_16x16x32_bf16 v[90:93], v[142:145], v[150:153], v[90:93]
	v_mfma_f32_16x16x32_bf16 v[86:89], v[134:137], v[158:161], v[86:89]
	v_mfma_f32_16x16x32_bf16 v[82:85], v[142:145], v[158:161], v[82:85]
	v_mfma_f32_16x16x32_bf16 v[78:81], v[134:137], v[166:169], v[78:81]
	v_mfma_f32_16x16x32_bf16 v[74:77], v[142:145], v[166:169], v[74:77]
	v_mfma_f32_16x16x32_bf16 v[70:73], v[134:137], v[186:189], v[70:73]
	v_mfma_f32_16x16x32_bf16 v[66:69], v[142:145], v[186:189], v[66:69]
	s_barrier
	s_add_u32 s12, s42, s18
	s_addc_u32 s13, s43, 0
	s_add_i32 s42, s92, s54
	v_lshl_add_u64 v[242:243], s[12:13], 0, v[170:171]
	s_mov_b32 m0, s42
	v_lshl_add_u64 v[244:245], s[12:13], 0, v[172:173]
	global_load_lds_dwordx4 v[242:243], off
	s_add_i32 m0, s42, 0x2000
	s_nop 0
	global_load_lds_dwordx4 v[244:245], off
	s_waitcnt vmcnt(6)
	s_barrier
	v_mfma_f32_16x16x32_bf16 v[30:33], v[190:193], v[146:149], v[30:33]
	v_mfma_f32_16x16x32_bf16 v[26:29], v[198:201], v[146:149], v[26:29]
	v_mfma_f32_16x16x32_bf16 v[22:25], v[190:193], v[154:157], v[22:25]
	v_mfma_f32_16x16x32_bf16 v[18:21], v[198:201], v[154:157], v[18:21]
	v_mfma_f32_16x16x32_bf16 v[14:17], v[190:193], v[162:165], v[14:17]
	v_mfma_f32_16x16x32_bf16 v[10:13], v[198:201], v[162:165], v[10:13]
	v_mfma_f32_16x16x32_bf16 v[6:9], v[190:193], v[178:181], v[6:9]
	v_mfma_f32_16x16x32_bf16 v[2:5], v[198:201], v[178:181], v[2:5]
	v_mfma_f32_16x16x32_bf16 v[30:33], v[194:197], v[150:153], v[30:33]
	v_mfma_f32_16x16x32_bf16 v[26:29], v[226:229], v[150:153], v[26:29]
	v_mfma_f32_16x16x32_bf16 v[22:25], v[194:197], v[158:161], v[22:25]
	v_mfma_f32_16x16x32_bf16 v[18:21], v[226:229], v[158:161], v[18:21]
	v_mfma_f32_16x16x32_bf16 v[14:17], v[194:197], v[166:169], v[14:17]
	v_mfma_f32_16x16x32_bf16 v[10:13], v[226:229], v[166:169], v[10:13]
	v_mfma_f32_16x16x32_bf16 v[6:9], v[194:197], v[186:189], v[6:9]
	v_mfma_f32_16x16x32_bf16 v[2:5], v[226:229], v[186:189], v[2:5]
	s_add_i32 s12, 0, 0x18000
	v_add_u32_e32 v142, s12, v183
	s_barrier
	ds_read_b128 v[130:133], v142
	ds_read_b128 v[134:137], v142 offset:1024
	ds_read_b128 v[138:141], v142 offset:2048
	ds_read_b128 v[142:145], v142 offset:3072
	s_add_u32 s2, s2, s18
	s_addc_u32 s3, s3, 0
	s_mov_b32 m0, s59
	v_lshl_add_u64 v[190:191], s[2:3], 0, v[170:171]
	ds_read_b128 v[146:149], v184 offset:32768
	ds_read_b128 v[150:153], v184 offset:33792
	ds_read_b128 v[154:157], v184 offset:34816
	ds_read_b128 v[158:161], v184 offset:35840
	ds_read_b128 v[162:165], v184 offset:36864
	ds_read_b128 v[166:169], v184 offset:37888
	ds_read_b128 v[178:181], v184 offset:38912
	ds_read_b128 v[186:189], v184 offset:39936
	global_load_lds_dwordx4 v[190:191], off
	v_lshl_add_u64 v[190:191], s[2:3], 0, v[172:173]
	s_mov_b32 m0, s77
	s_nop 0
	global_load_lds_dwordx4 v[190:191], off
	s_waitcnt lgkmcnt(8)
	s_barrier
	s_waitcnt lgkmcnt(0)
	s_waitcnt lgkmcnt(0)
	v_mfma_f32_16x16x32_bf16 v[126:129], v[130:133], v[146:149], v[126:129]
	v_mfma_f32_16x16x32_bf16 v[122:125], v[138:141], v[146:149], v[122:125]
	v_mfma_f32_16x16x32_bf16 v[118:121], v[130:133], v[154:157], v[118:121]
	v_mfma_f32_16x16x32_bf16 v[114:117], v[138:141], v[154:157], v[114:117]
	v_mfma_f32_16x16x32_bf16 v[110:113], v[130:133], v[162:165], v[110:113]
	v_mfma_f32_16x16x32_bf16 v[106:109], v[138:141], v[162:165], v[106:109]
	v_mfma_f32_16x16x32_bf16 v[102:105], v[130:133], v[178:181], v[102:105]
	v_mfma_f32_16x16x32_bf16 v[98:101], v[138:141], v[178:181], v[98:101]
	v_mfma_f32_16x16x32_bf16 v[126:129], v[134:137], v[150:153], v[126:129]
	v_mfma_f32_16x16x32_bf16 v[122:125], v[142:145], v[150:153], v[122:125]
	v_mfma_f32_16x16x32_bf16 v[118:121], v[134:137], v[158:161], v[118:121]
	v_mfma_f32_16x16x32_bf16 v[114:117], v[142:145], v[158:161], v[114:117]
	v_mfma_f32_16x16x32_bf16 v[110:113], v[134:137], v[166:169], v[110:113]
	v_mfma_f32_16x16x32_bf16 v[106:109], v[142:145], v[166:169], v[106:109]
	v_mfma_f32_16x16x32_bf16 v[102:105], v[134:137], v[186:189], v[102:105]
	v_mfma_f32_16x16x32_bf16 v[98:101], v[142:145], v[186:189], v[98:101]
	s_barrier
	s_add_i32 s2, 0, 0x1c000
	s_add_i32 s3, s12, s54
	v_add_u32_e32 v185, s2, v183
	v_lshl_add_u64 v[230:231], v[230:231], 0, s[20:21]
	s_mov_b32 m0, s3
	ds_read_b128 v[190:193], v185
	ds_read_b128 v[194:197], v185 offset:1024
	ds_read_b128 v[198:201], v185 offset:2048
	ds_read_b128 v[226:229], v185 offset:3072
	global_load_lds_dwordx4 v[230:231], off
	v_lshl_add_u64 v[230:231], v[232:233], 0, s[20:21]
	s_add_i32 m0, s3, 0x2000
	s_nop 0
	global_load_lds_dwordx4 v[230:231], off
	s_barrier
	s_waitcnt lgkmcnt(0)
	s_waitcnt lgkmcnt(0)
	v_mfma_f32_16x16x32_bf16 v[62:65], v[190:193], v[146:149], v[62:65]
	v_mfma_f32_16x16x32_bf16 v[58:61], v[198:201], v[146:149], v[58:61]
	v_mfma_f32_16x16x32_bf16 v[54:57], v[190:193], v[154:157], v[54:57]
	v_mfma_f32_16x16x32_bf16 v[50:53], v[198:201], v[154:157], v[50:53]
	v_mfma_f32_16x16x32_bf16 v[46:49], v[190:193], v[162:165], v[46:49]
	v_mfma_f32_16x16x32_bf16 v[42:45], v[198:201], v[162:165], v[42:45]
	v_mfma_f32_16x16x32_bf16 v[38:41], v[190:193], v[178:181], v[38:41]
	v_mfma_f32_16x16x32_bf16 v[34:37], v[198:201], v[178:181], v[34:37]
	v_mfma_f32_16x16x32_bf16 v[62:65], v[194:197], v[150:153], v[62:65]
	v_mfma_f32_16x16x32_bf16 v[58:61], v[226:229], v[150:153], v[58:61]
	v_mfma_f32_16x16x32_bf16 v[54:57], v[194:197], v[158:161], v[54:57]
	v_mfma_f32_16x16x32_bf16 v[50:53], v[226:229], v[158:161], v[50:53]
	v_mfma_f32_16x16x32_bf16 v[46:49], v[194:197], v[166:169], v[46:49]
	v_mfma_f32_16x16x32_bf16 v[42:45], v[226:229], v[166:169], v[42:45]
	v_mfma_f32_16x16x32_bf16 v[38:41], v[194:197], v[186:189], v[38:41]
	v_mfma_f32_16x16x32_bf16 v[34:37], v[226:229], v[186:189], v[34:37]
	s_mov_b32 m0, s80
	v_lshl_add_u64 v[230:231], v[234:235], 0, s[20:21]
	s_barrier
	ds_read_b128 v[146:149], v184 offset:49152
	ds_read_b128 v[150:153], v184 offset:50176
	ds_read_b128 v[154:157], v184 offset:51200
	ds_read_b128 v[158:161], v184 offset:52224
	ds_read_b128 v[162:165], v184 offset:53248
	ds_read_b128 v[166:169], v184 offset:54272
	ds_read_b128 v[178:181], v184 offset:55296
	ds_read_b128 v[186:189], v184 offset:56320
	global_load_lds_dwordx4 v[230:231], off
	v_lshl_add_u64 v[230:231], v[236:237], 0, s[20:21]
	s_mov_b32 m0, s81
	s_nop 0
	global_load_lds_dwordx4 v[230:231], off
	s_barrier
	s_waitcnt lgkmcnt(0)
	s_waitcnt lgkmcnt(0)
	v_mfma_f32_16x16x32_bf16 v[94:97], v[130:133], v[146:149], v[94:97]
	v_mfma_f32_16x16x32_bf16 v[90:93], v[138:141], v[146:149], v[90:93]
	v_mfma_f32_16x16x32_bf16 v[86:89], v[130:133], v[154:157], v[86:89]
	v_mfma_f32_16x16x32_bf16 v[82:85], v[138:141], v[154:157], v[82:85]
	v_mfma_f32_16x16x32_bf16 v[78:81], v[130:133], v[162:165], v[78:81]
	v_mfma_f32_16x16x32_bf16 v[74:77], v[138:141], v[162:165], v[74:77]
	v_mfma_f32_16x16x32_bf16 v[70:73], v[130:133], v[178:181], v[70:73]
	v_mfma_f32_16x16x32_bf16 v[66:69], v[138:141], v[178:181], v[66:69]
	v_mfma_f32_16x16x32_bf16 v[94:97], v[134:137], v[150:153], v[94:97]
	v_mfma_f32_16x16x32_bf16 v[90:93], v[142:145], v[150:153], v[90:93]
	v_mfma_f32_16x16x32_bf16 v[86:89], v[134:137], v[158:161], v[86:89]
	v_mfma_f32_16x16x32_bf16 v[82:85], v[142:145], v[158:161], v[82:85]
	v_mfma_f32_16x16x32_bf16 v[78:81], v[134:137], v[166:169], v[78:81]
	v_mfma_f32_16x16x32_bf16 v[74:77], v[142:145], v[166:169], v[74:77]
	v_mfma_f32_16x16x32_bf16 v[70:73], v[134:137], v[186:189], v[70:73]
	v_mfma_f32_16x16x32_bf16 v[66:69], v[142:145], v[186:189], v[66:69]
	s_barrier
	s_add_i32 s2, s2, s54
	v_lshl_add_u64 v[130:131], v[242:243], 0, s[20:21]
	s_mov_b32 m0, s2
	s_nop 0
	global_load_lds_dwordx4 v[130:131], off
	v_lshl_add_u64 v[130:131], v[244:245], 0, s[20:21]
	s_add_i32 m0, s2, 0x2000
	s_nop 0
	global_load_lds_dwordx4 v[130:131], off
	s_waitcnt vmcnt(6)
	s_barrier
	v_mfma_f32_16x16x32_bf16 v[30:33], v[190:193], v[146:149], v[30:33]
	v_mfma_f32_16x16x32_bf16 v[26:29], v[198:201], v[146:149], v[26:29]
	v_mfma_f32_16x16x32_bf16 v[22:25], v[190:193], v[154:157], v[22:25]
	v_mfma_f32_16x16x32_bf16 v[18:21], v[198:201], v[154:157], v[18:21]
	v_mfma_f32_16x16x32_bf16 v[14:17], v[190:193], v[162:165], v[14:17]
	v_mfma_f32_16x16x32_bf16 v[10:13], v[198:201], v[162:165], v[10:13]
	v_mfma_f32_16x16x32_bf16 v[6:9], v[190:193], v[178:181], v[6:9]
	v_mfma_f32_16x16x32_bf16 v[2:5], v[198:201], v[178:181], v[2:5]
	v_mfma_f32_16x16x32_bf16 v[30:33], v[194:197], v[150:153], v[30:33]
	v_mfma_f32_16x16x32_bf16 v[26:29], v[226:229], v[150:153], v[26:29]
	v_mfma_f32_16x16x32_bf16 v[22:25], v[194:197], v[158:161], v[22:25]
	v_mfma_f32_16x16x32_bf16 v[18:21], v[226:229], v[158:161], v[18:21]
	v_mfma_f32_16x16x32_bf16 v[14:17], v[194:197], v[166:169], v[14:17]
	v_mfma_f32_16x16x32_bf16 v[10:13], v[226:229], v[166:169], v[10:13]
	v_mfma_f32_16x16x32_bf16 v[6:9], v[194:197], v[186:189], v[6:9]
	v_mfma_f32_16x16x32_bf16 v[2:5], v[226:229], v[186:189], v[2:5]
	s_add_u32 s34, s34, 0x100
	s_addc_u32 s35, s35, 0
	s_add_u32 s89, s89, 0x100
	s_addc_u32 s90, s90, 0
	s_cmp_ge_i32 s91, s44
	s_mov_b32 s2, s91
	s_barrier
	s_cbranch_scc0 .LBB0_182
	s_cmp_lt_i32 s86, 64
	s_cselect_b64 s[34:35], -1, 0
	s_ashr_i32 s2, s45, 8
	s_ashr_i32 s3, s2, 31
	s_lshl_b64 s[2:3], s[2:3], 18
	s_add_u32 s2, s2, 0x3232000
	s_addc_u32 s3, s3, 0
	s_cmp_gt_i32 s86, 63
	s_cselect_b32 s12, 0x6000, 0
	s_cselect_b32 s45, s3, 0
	s_cselect_b32 s44, s2, 0
	s_add_u32 s12, s78, s12
	s_addc_u32 s13, s79, 0
	s_lshl_b32 s2, s87, 8
	s_ashr_i32 s3, s2, 31
	s_lshl_b64 s[2:3], s[2:3], 2
	s_add_u32 s12, s12, s2
	s_addc_u32 s13, s13, s3
	v_readlane_b32 s88, v254, 38
	s_add_u32 s42, s12, s88
	s_addc_u32 s43, s13, 0
	global_load_dwordx4 v[134:137], v0, s[42:43]
	global_load_dwordx4 v[130:133], v0, s[42:43] offset:64
	v_lshl_add_u32 v138, s86, 8, v182
	v_ashrrev_i32_e32 v139, 31, v138
	v_readlane_b32 s12, v252, 5
	v_lshlrev_b64 v[138:139], 12, v[138:139]
	v_readlane_b32 s13, v252, 6
	v_readlane_b32 s89, v254, 39
	s_and_b64 vcc, exec, s[34:35]
	v_lshl_add_u64 v[138:139], s[12:13], 0, v[138:139]
	v_lshl_add_u64 v[138:139], v[138:139], 0, s[2:3]
	v_lshl_add_u64 v[138:139], v[138:139], 0, s[88:89]
	v_lshl_add_u64 v[178:179], v[138:139], 0, v[0:1]
	v_lshl_add_u64 v[180:181], v[178:179], 0, s[22:23]
	v_readfirstlane_b32 s88, v178
	v_readfirstlane_b32 s89, v179
	v_and_b32_e32 v178, 15, v202
	v_bfe_u32 v179, v202, 4, 2
	v_lshlrev_b32_e32 v178, 12, v178
	v_lshl_or_b32 v178, v179, 4, v178
	s_and_b64 vcc, exec, s[34:35]
	s_cbranch_vccz .Lre0_split
	s_add_u32 s2, s88, s22
	s_addc_u32 s3, s89, s23
	s_nop 1
	global_load_dwordx4 v[138:141], v178, s[2:3] offset:0
	global_load_dwordx4 v[142:145], v178, s[2:3] offset:64
	s_add_u32 s2, s2, 0x10000
	s_addc_u32 s3, s3, 0
	global_load_dwordx4 v[146:149], v178, s[2:3] offset:0
	global_load_dwordx4 v[150:153], v178, s[2:3] offset:64
	s_add_u32 s2, s2, 0x10000
	s_addc_u32 s3, s3, 0
	global_load_dwordx4 v[154:157], v178, s[2:3] offset:0
	global_load_dwordx4 v[158:161], v178, s[2:3] offset:64
	s_add_u32 s2, s2, 0x10000
	s_addc_u32 s3, s3, 0
	global_load_dwordx4 v[162:165], v178, s[2:3] offset:0
	global_load_dwordx4 v[166:169], v178, s[2:3] offset:64
	s_add_u32 s2, s2, 0x50000
	s_addc_u32 s3, s3, 0
	global_load_dwordx4 v[186:189], v178, s[2:3] offset:0
	global_load_dwordx4 v[190:193], v178, s[2:3] offset:64
	s_add_u32 s2, s2, 0x10000
	s_addc_u32 s3, s3, 0
	global_load_dwordx4 v[194:197], v178, s[2:3] offset:0
	global_load_dwordx4 v[198:201], v178, s[2:3] offset:64
	s_add_u32 s2, s2, 0x10000
	s_addc_u32 s3, s3, 0
	global_load_dwordx4 v[226:229], v178, s[2:3] offset:0
	global_load_dwordx4 v[230:233], v178, s[2:3] offset:64
	s_add_u32 s2, s2, 0x10000
	s_addc_u32 s3, s3, 0
	global_load_dwordx4 v[234:237], v178, s[2:3] offset:0
	global_load_dwordx4 v[242:245], v178, s[2:3] offset:64
	s_mov_b32 s2, s88
	s_mov_b32 s3, s89
	s_waitcnt vmcnt(0)
	v_pk_fma_f32 v[126:127], v[126:127], v[134:135], v[138:139]
	v_pk_fma_f32 v[128:129], v[128:129], v[136:137], v[140:141]
	v_pk_fma_f32 v[122:123], v[122:123], v[130:131], v[142:143]
	v_pk_fma_f32 v[124:125], v[124:125], v[132:133], v[144:145]
	v_pk_fma_f32 v[118:119], v[118:119], v[134:135], v[146:147]
	v_pk_fma_f32 v[120:121], v[120:121], v[136:137], v[148:149]
	v_pk_fma_f32 v[114:115], v[114:115], v[130:131], v[150:151]
	v_pk_fma_f32 v[116:117], v[116:117], v[132:133], v[152:153]
	v_pk_fma_f32 v[110:111], v[110:111], v[134:135], v[154:155]
	v_pk_fma_f32 v[112:113], v[112:113], v[136:137], v[156:157]
	v_pk_fma_f32 v[106:107], v[106:107], v[130:131], v[158:159]
	v_pk_fma_f32 v[108:109], v[108:109], v[132:133], v[160:161]
	v_pk_fma_f32 v[102:103], v[102:103], v[134:135], v[162:163]
	v_pk_fma_f32 v[104:105], v[104:105], v[136:137], v[164:165]
	v_pk_fma_f32 v[98:99], v[98:99], v[130:131], v[166:167]
	v_pk_fma_f32 v[100:101], v[100:101], v[132:133], v[168:169]
	v_pk_fma_f32 v[94:95], v[94:95], v[134:135], v[186:187]
	v_pk_fma_f32 v[96:97], v[96:97], v[136:137], v[188:189]
	v_pk_fma_f32 v[90:91], v[90:91], v[130:131], v[190:191]
	v_pk_fma_f32 v[92:93], v[92:93], v[132:133], v[192:193]
	v_pk_fma_f32 v[86:87], v[86:87], v[134:135], v[194:195]
	v_pk_fma_f32 v[88:89], v[88:89], v[136:137], v[196:197]
	v_pk_fma_f32 v[82:83], v[82:83], v[130:131], v[198:199]
	v_pk_fma_f32 v[84:85], v[84:85], v[132:133], v[200:201]
	v_pk_fma_f32 v[78:79], v[78:79], v[134:135], v[226:227]
	v_pk_fma_f32 v[80:81], v[80:81], v[136:137], v[228:229]
	v_pk_fma_f32 v[74:75], v[74:75], v[130:131], v[230:231]
	v_pk_fma_f32 v[76:77], v[76:77], v[132:133], v[232:233]
	v_pk_fma_f32 v[70:71], v[70:71], v[134:135], v[234:235]
	v_pk_fma_f32 v[72:73], v[72:73], v[136:137], v[236:237]
	v_pk_fma_f32 v[66:67], v[66:67], v[130:131], v[242:243]
	v_pk_fma_f32 v[68:69], v[68:69], v[132:133], v[244:245]
	global_store_dwordx4 v178, v[126:129], s[2:3] offset:0
	global_store_dwordx4 v178, v[122:125], s[2:3] offset:64
	s_add_u32 s2, s2, 0x10000
	s_addc_u32 s3, s3, 0
	global_store_dwordx4 v178, v[118:121], s[2:3] offset:0
	global_store_dwordx4 v178, v[114:117], s[2:3] offset:64
	s_add_u32 s2, s2, 0x10000
	s_addc_u32 s3, s3, 0
	global_store_dwordx4 v178, v[110:113], s[2:3] offset:0
	global_store_dwordx4 v178, v[106:109], s[2:3] offset:64
	s_add_u32 s2, s2, 0x10000
	s_addc_u32 s3, s3, 0
	global_store_dwordx4 v178, v[102:105], s[2:3] offset:0
	global_store_dwordx4 v178, v[98:101], s[2:3] offset:64
	s_add_u32 s2, s2, 0x50000
	s_addc_u32 s3, s3, 0
	global_store_dwordx4 v178, v[94:97], s[2:3] offset:0
	global_store_dwordx4 v178, v[90:93], s[2:3] offset:64
	s_add_u32 s2, s2, 0x10000
	s_addc_u32 s3, s3, 0
	global_store_dwordx4 v178, v[86:89], s[2:3] offset:0
	global_store_dwordx4 v178, v[82:85], s[2:3] offset:64
	s_add_u32 s2, s2, 0x10000
	s_addc_u32 s3, s3, 0
	global_store_dwordx4 v178, v[78:81], s[2:3] offset:0
	global_store_dwordx4 v178, v[74:77], s[2:3] offset:64
	s_add_u32 s2, s2, 0x10000
	s_addc_u32 s3, s3, 0
	global_store_dwordx4 v178, v[70:73], s[2:3] offset:0
	global_store_dwordx4 v178, v[66:69], s[2:3] offset:64
	s_branch .Lre0_done
.Lre0_split:
	s_lshl_b64 s[2:3], s[44:45], 2
	s_add_u32 s2, s2, s88
	s_addc_u32 s3, s3, s89
	s_waitcnt vmcnt(0)
	v_pk_mul_f32 v[126:127], v[126:127], v[134:135]
	v_pk_mul_f32 v[128:129], v[128:129], v[136:137]
	v_pk_mul_f32 v[122:123], v[122:123], v[130:131]
	v_pk_mul_f32 v[124:125], v[124:125], v[132:133]
	v_pk_mul_f32 v[118:119], v[118:119], v[134:135]
	v_pk_mul_f32 v[120:121], v[120:121], v[136:137]
	v_pk_mul_f32 v[114:115], v[114:115], v[130:131]
	v_pk_mul_f32 v[116:117], v[116:117], v[132:133]
	v_pk_mul_f32 v[110:111], v[110:111], v[134:135]
	v_pk_mul_f32 v[112:113], v[112:113], v[136:137]
	v_pk_mul_f32 v[106:107], v[106:107], v[130:131]
	v_pk_mul_f32 v[108:109], v[108:109], v[132:133]
	v_pk_mul_f32 v[102:103], v[102:103], v[134:135]
	v_pk_mul_f32 v[104:105], v[104:105], v[136:137]
	v_pk_mul_f32 v[98:99], v[98:99], v[130:131]
	v_pk_mul_f32 v[100:101], v[100:101], v[132:133]
	v_pk_mul_f32 v[94:95], v[94:95], v[134:135]
	v_pk_mul_f32 v[96:97], v[96:97], v[136:137]
	v_pk_mul_f32 v[90:91], v[90:91], v[130:131]
	v_pk_mul_f32 v[92:93], v[92:93], v[132:133]
	v_pk_mul_f32 v[86:87], v[86:87], v[134:135]
	v_pk_mul_f32 v[88:89], v[88:89], v[136:137]
	v_pk_mul_f32 v[82:83], v[82:83], v[130:131]
	v_pk_mul_f32 v[84:85], v[84:85], v[132:133]
	v_pk_mul_f32 v[78:79], v[78:79], v[134:135]
	v_pk_mul_f32 v[80:81], v[80:81], v[136:137]
	v_pk_mul_f32 v[74:75], v[74:75], v[130:131]
	v_pk_mul_f32 v[76:77], v[76:77], v[132:133]
	v_pk_mul_f32 v[70:71], v[70:71], v[134:135]
	v_pk_mul_f32 v[72:73], v[72:73], v[136:137]
	v_pk_mul_f32 v[66:67], v[66:67], v[130:131]
	v_pk_mul_f32 v[68:69], v[68:69], v[132:133]
	global_store_dwordx4 v178, v[126:129], s[2:3] offset:0
	global_store_dwordx4 v178, v[122:125], s[2:3] offset:64
	s_add_u32 s2, s2, 0x10000
	s_addc_u32 s3, s3, 0
	global_store_dwordx4 v178, v[118:121], s[2:3] offset:0
	global_store_dwordx4 v178, v[114:117], s[2:3] offset:64
	s_add_u32 s2, s2, 0x10000
	s_addc_u32 s3, s3, 0
	global_store_dwordx4 v178, v[110:113], s[2:3] offset:0
	global_store_dwordx4 v178, v[106:109], s[2:3] offset:64
	s_add_u32 s2, s2, 0x10000
	s_addc_u32 s3, s3, 0
	global_store_dwordx4 v178, v[102:105], s[2:3] offset:0
	global_store_dwordx4 v178, v[98:101], s[2:3] offset:64
	s_add_u32 s2, s2, 0x50000
	s_addc_u32 s3, s3, 0
	global_store_dwordx4 v178, v[94:97], s[2:3] offset:0
	global_store_dwordx4 v178, v[90:93], s[2:3] offset:64
	s_add_u32 s2, s2, 0x10000
	s_addc_u32 s3, s3, 0
	global_store_dwordx4 v178, v[86:89], s[2:3] offset:0
	global_store_dwordx4 v178, v[82:85], s[2:3] offset:64
	s_add_u32 s2, s2, 0x10000
	s_addc_u32 s3, s3, 0
	global_store_dwordx4 v178, v[78:81], s[2:3] offset:0
	global_store_dwordx4 v178, v[74:77], s[2:3] offset:64
	s_add_u32 s2, s2, 0x10000
	s_addc_u32 s3, s3, 0
	global_store_dwordx4 v178, v[70:73], s[2:3] offset:0
	global_store_dwordx4 v178, v[66:69], s[2:3] offset:64
.Lre0_done:
	global_load_dwordx4 v[134:137], v0, s[42:43] offset:512
	global_load_dwordx4 v[130:133], v0, s[42:43] offset:576
	s_and_b64 vcc, exec, s[34:35]
	s_cbranch_vccz .Lre1_split
	s_add_u32 s2, s88, s22
	s_addc_u32 s3, s89, s23
	s_nop 1
	global_load_dwordx4 v[138:141], v178, s[2:3] offset:512
	global_load_dwordx4 v[142:145], v178, s[2:3] offset:576
	s_add_u32 s2, s2, 0x10000
	s_addc_u32 s3, s3, 0
	global_load_dwordx4 v[146:149], v178, s[2:3] offset:512
	global_load_dwordx4 v[150:153], v178, s[2:3] offset:576
	s_add_u32 s2, s2, 0x10000
	s_addc_u32 s3, s3, 0
	global_load_dwordx4 v[154:157], v178, s[2:3] offset:512
	global_load_dwordx4 v[158:161], v178, s[2:3] offset:576
	s_add_u32 s2, s2, 0x10000
	s_addc_u32 s3, s3, 0
	global_load_dwordx4 v[162:165], v178, s[2:3] offset:512
	global_load_dwordx4 v[166:169], v178, s[2:3] offset:576
	s_add_u32 s2, s2, 0x50000
	s_addc_u32 s3, s3, 0
	global_load_dwordx4 v[186:189], v178, s[2:3] offset:512
	global_load_dwordx4 v[190:193], v178, s[2:3] offset:576
	s_add_u32 s2, s2, 0x10000
	s_addc_u32 s3, s3, 0
	global_load_dwordx4 v[194:197], v178, s[2:3] offset:512
	global_load_dwordx4 v[198:201], v178, s[2:3] offset:576
	s_add_u32 s2, s2, 0x10000
	s_addc_u32 s3, s3, 0
	global_load_dwordx4 v[226:229], v178, s[2:3] offset:512
	global_load_dwordx4 v[230:233], v178, s[2:3] offset:576
	s_add_u32 s2, s2, 0x10000
	s_addc_u32 s3, s3, 0
	global_load_dwordx4 v[234:237], v178, s[2:3] offset:512
	global_load_dwordx4 v[242:245], v178, s[2:3] offset:576
	s_mov_b32 s2, s88
	s_mov_b32 s3, s89
	s_waitcnt vmcnt(0)
	v_pk_fma_f32 v[62:63], v[62:63], v[134:135], v[138:139]
	v_pk_fma_f32 v[64:65], v[64:65], v[136:137], v[140:141]
	v_pk_fma_f32 v[58:59], v[58:59], v[130:131], v[142:143]
	v_pk_fma_f32 v[60:61], v[60:61], v[132:133], v[144:145]
	v_pk_fma_f32 v[54:55], v[54:55], v[134:135], v[146:147]
	v_pk_fma_f32 v[56:57], v[56:57], v[136:137], v[148:149]
	v_pk_fma_f32 v[50:51], v[50:51], v[130:131], v[150:151]
	v_pk_fma_f32 v[52:53], v[52:53], v[132:133], v[152:153]
	v_pk_fma_f32 v[46:47], v[46:47], v[134:135], v[154:155]
	v_pk_fma_f32 v[48:49], v[48:49], v[136:137], v[156:157]
	v_pk_fma_f32 v[42:43], v[42:43], v[130:131], v[158:159]
	v_pk_fma_f32 v[44:45], v[44:45], v[132:133], v[160:161]
	v_pk_fma_f32 v[38:39], v[38:39], v[134:135], v[162:163]
	v_pk_fma_f32 v[40:41], v[40:41], v[136:137], v[164:165]
	v_pk_fma_f32 v[34:35], v[34:35], v[130:131], v[166:167]
	v_pk_fma_f32 v[36:37], v[36:37], v[132:133], v[168:169]
	v_pk_fma_f32 v[30:31], v[30:31], v[134:135], v[186:187]
	v_pk_fma_f32 v[32:33], v[32:33], v[136:137], v[188:189]
	v_pk_fma_f32 v[26:27], v[26:27], v[130:131], v[190:191]
	v_pk_fma_f32 v[28:29], v[28:29], v[132:133], v[192:193]
	v_pk_fma_f32 v[22:23], v[22:23], v[134:135], v[194:195]
	v_pk_fma_f32 v[24:25], v[24:25], v[136:137], v[196:197]
	v_pk_fma_f32 v[18:19], v[18:19], v[130:131], v[198:199]
	v_pk_fma_f32 v[20:21], v[20:21], v[132:133], v[200:201]
	v_pk_fma_f32 v[14:15], v[14:15], v[134:135], v[226:227]
	v_pk_fma_f32 v[16:17], v[16:17], v[136:137], v[228:229]
	v_pk_fma_f32 v[10:11], v[10:11], v[130:131], v[230:231]
	v_pk_fma_f32 v[12:13], v[12:13], v[132:133], v[232:233]
	v_pk_fma_f32 v[6:7], v[6:7], v[134:135], v[234:235]
	v_pk_fma_f32 v[8:9], v[8:9], v[136:137], v[236:237]
	v_pk_fma_f32 v[2:3], v[2:3], v[130:131], v[242:243]
	v_pk_fma_f32 v[4:5], v[4:5], v[132:133], v[244:245]
	global_store_dwordx4 v178, v[62:65], s[2:3] offset:512
	global_store_dwordx4 v178, v[58:61], s[2:3] offset:576
	s_add_u32 s2, s2, 0x10000
	s_addc_u32 s3, s3, 0
	global_store_dwordx4 v178, v[54:57], s[2:3] offset:512
	global_store_dwordx4 v178, v[50:53], s[2:3] offset:576
	s_add_u32 s2, s2, 0x10000
	s_addc_u32 s3, s3, 0
	global_store_dwordx4 v178, v[46:49], s[2:3] offset:512
	global_store_dwordx4 v178, v[42:45], s[2:3] offset:576
	s_add_u32 s2, s2, 0x10000
	s_addc_u32 s3, s3, 0
	global_store_dwordx4 v178, v[38:41], s[2:3] offset:512
	global_store_dwordx4 v178, v[34:37], s[2:3] offset:576
	s_add_u32 s2, s2, 0x50000
	s_addc_u32 s3, s3, 0
	global_store_dwordx4 v178, v[30:33], s[2:3] offset:512
	global_store_dwordx4 v178, v[26:29], s[2:3] offset:576
	s_add_u32 s2, s2, 0x10000
	s_addc_u32 s3, s3, 0
	global_store_dwordx4 v178, v[22:25], s[2:3] offset:512
	global_store_dwordx4 v178, v[18:21], s[2:3] offset:576
	s_add_u32 s2, s2, 0x10000
	s_addc_u32 s3, s3, 0
	global_store_dwordx4 v178, v[14:17], s[2:3] offset:512
	global_store_dwordx4 v178, v[10:13], s[2:3] offset:576
	s_add_u32 s2, s2, 0x10000
	s_addc_u32 s3, s3, 0
	global_store_dwordx4 v178, v[6:9], s[2:3] offset:512
	global_store_dwordx4 v178, v[2:5], s[2:3] offset:576
	s_branch .Lre1_done
.Lre1_split:
	s_lshl_b64 s[2:3], s[44:45], 2
	s_add_u32 s2, s2, s88
	s_addc_u32 s3, s3, s89
	s_waitcnt vmcnt(0)
	v_pk_mul_f32 v[62:63], v[62:63], v[134:135]
	v_pk_mul_f32 v[64:65], v[64:65], v[136:137]
	v_pk_mul_f32 v[58:59], v[58:59], v[130:131]
	v_pk_mul_f32 v[60:61], v[60:61], v[132:133]
	v_pk_mul_f32 v[54:55], v[54:55], v[134:135]
	v_pk_mul_f32 v[56:57], v[56:57], v[136:137]
	v_pk_mul_f32 v[50:51], v[50:51], v[130:131]
	v_pk_mul_f32 v[52:53], v[52:53], v[132:133]
	v_pk_mul_f32 v[46:47], v[46:47], v[134:135]
	v_pk_mul_f32 v[48:49], v[48:49], v[136:137]
	v_pk_mul_f32 v[42:43], v[42:43], v[130:131]
	v_pk_mul_f32 v[44:45], v[44:45], v[132:133]
	v_pk_mul_f32 v[38:39], v[38:39], v[134:135]
	v_pk_mul_f32 v[40:41], v[40:41], v[136:137]
	v_pk_mul_f32 v[34:35], v[34:35], v[130:131]
	v_pk_mul_f32 v[36:37], v[36:37], v[132:133]
	v_pk_mul_f32 v[30:31], v[30:31], v[134:135]
	v_pk_mul_f32 v[32:33], v[32:33], v[136:137]
	v_pk_mul_f32 v[26:27], v[26:27], v[130:131]
	v_pk_mul_f32 v[28:29], v[28:29], v[132:133]
	v_pk_mul_f32 v[22:23], v[22:23], v[134:135]
	v_pk_mul_f32 v[24:25], v[24:25], v[136:137]
	v_pk_mul_f32 v[18:19], v[18:19], v[130:131]
	v_pk_mul_f32 v[20:21], v[20:21], v[132:133]
	v_pk_mul_f32 v[14:15], v[14:15], v[134:135]
	v_pk_mul_f32 v[16:17], v[16:17], v[136:137]
	v_pk_mul_f32 v[10:11], v[10:11], v[130:131]
	v_pk_mul_f32 v[12:13], v[12:13], v[132:133]
	v_pk_mul_f32 v[6:7], v[6:7], v[134:135]
	v_pk_mul_f32 v[8:9], v[8:9], v[136:137]
	v_pk_mul_f32 v[2:3], v[2:3], v[130:131]
	v_pk_mul_f32 v[4:5], v[4:5], v[132:133]
	global_store_dwordx4 v178, v[62:65], s[2:3] offset:512
	global_store_dwordx4 v178, v[58:61], s[2:3] offset:576
	s_add_u32 s2, s2, 0x10000
	s_addc_u32 s3, s3, 0
	global_store_dwordx4 v178, v[54:57], s[2:3] offset:512
	global_store_dwordx4 v178, v[50:53], s[2:3] offset:576
	s_add_u32 s2, s2, 0x10000
	s_addc_u32 s3, s3, 0
	global_store_dwordx4 v178, v[46:49], s[2:3] offset:512
	global_store_dwordx4 v178, v[42:45], s[2:3] offset:576
	s_add_u32 s2, s2, 0x10000
	s_addc_u32 s3, s3, 0
	global_store_dwordx4 v178, v[38:41], s[2:3] offset:512
	global_store_dwordx4 v178, v[34:37], s[2:3] offset:576
	s_add_u32 s2, s2, 0x50000
	s_addc_u32 s3, s3, 0
	global_store_dwordx4 v178, v[30:33], s[2:3] offset:512
	global_store_dwordx4 v178, v[26:29], s[2:3] offset:576
	s_add_u32 s2, s2, 0x10000
	s_addc_u32 s3, s3, 0
	global_store_dwordx4 v178, v[22:25], s[2:3] offset:512
	global_store_dwordx4 v178, v[18:21], s[2:3] offset:576
	s_add_u32 s2, s2, 0x10000
	s_addc_u32 s3, s3, 0
	global_store_dwordx4 v178, v[14:17], s[2:3] offset:512
	global_store_dwordx4 v178, v[10:13], s[2:3] offset:576
	s_add_u32 s2, s2, 0x10000
	s_addc_u32 s3, s3, 0
	global_store_dwordx4 v178, v[6:9], s[2:3] offset:512
	global_store_dwordx4 v178, v[2:5], s[2:3] offset:576
.Lre1_done:
	s_and_b64 vcc, exec, s[34:35]
	s_cbranch_vccz .Lfz_skip
	v_readlane_b32 s2, v252, 2
	v_readlane_b32 s3, v255, 14
	v_readlane_b32 s89, v255, 12
	s_cmp_eq_u32 s2, 0x100
	s_cbranch_scc0 .Lfz_skip
	s_cmp_eq_u32 s3, 5
	s_cbranch_scc1 .Lfz_go
	s_cmp_eq_u32 s3, 8
	s_cbranch_scc0 .Lfz_skip
	s_cmp_lt_u32 s89, 3
	s_cbranch_scc0 .Lfz_skip
.Lfz_go:
	s_cmpk_gt_u32 s49, 0xff
	s_cbranch_scc1 .Lfz_al
	s_barrier
.Lfz_al:
	s_cmp_eq_u32 s3, 5
	s_cselect_b32 s2, 0, 1
	s_lshl_b32 s88, s89, 1
	s_add_i32 s88, s88, s2
	s_add_i32 s88, s88, 1
	s_lshl_b32 s88, s88, 2
	s_add_i32 s89, s89, s2
	v_readlane_b32 s12, v254, 21
	v_readlane_b32 s13, v254, 22
	v_readlane_b32 s42, v254, 54
	v_readlane_b32 s43, v254, 55
	s_cmp_eq_u32 s3, 5
	s_cselect_b32 s12, s12, s42
	s_cselect_b32 s13, s13, s43
	s_cselect_b32 s3, 0x3000, 0
	s_lshr_b32 s2, s49, 6
	s_and_b32 s2, s2, 3
	s_lshl_b32 s2, s2, 7
	s_lshl_b32 s42, s87, 10
	s_add_i32 s2, s2, s42
	s_lshl_b32 s42, s89, 12
	s_add_i32 s42, s42, s2
	s_add_u32 s12, s12, s42
	s_addc_u32 s13, s13, 0
	v_readlane_b32 s42, v252, 11
	v_readlane_b32 s43, v252, 12
	s_mul_i32 s44, s89, 0xc000
	s_add_i32 s44, s44, s3
	s_add_i32 s44, s44, s2
	s_add_u32 s42, s42, s44
	s_addc_u32 s43, s43, 0
	s_add_u32 s44, s42, 0x1000
	s_addc_u32 s45, s43, 0
	v_lshlrev_b32_e32 v180, 4, v179
	s_nop 1
	global_load_dwordx4 v[130:133], v180, s[12:13]
	global_load_dwordx4 v[146:149], v180, s[44:45]
	global_load_dwordx4 v[186:189], v180, s[42:43]
	global_load_dwordx4 v[134:137], v180, s[12:13] offset:64
	global_load_dwordx4 v[150:153], v180, s[44:45] offset:64
	global_load_dwordx4 v[190:193], v180, s[42:43] offset:64
	global_load_dwordx4 v[138:141], v180, s[12:13] offset:512
	global_load_dwordx4 v[154:157], v180, s[44:45] offset:512
	global_load_dwordx4 v[194:197], v180, s[42:43] offset:512
	global_load_dwordx4 v[142:145], v180, s[12:13] offset:576
	global_load_dwordx4 v[158:161], v180, s[44:45] offset:576
	global_load_dwordx4 v[198:201], v180, s[42:43] offset:576
	v_mul_f32_e32 v226, v126, v126
	v_fmac_f32_e32 v226, v127, v127
	v_fmac_f32_e32 v226, v128, v128
	v_fmac_f32_e32 v226, v129, v129
	v_fmac_f32_e32 v226, v122, v122
	v_fmac_f32_e32 v226, v123, v123
	v_fmac_f32_e32 v226, v124, v124
	v_fmac_f32_e32 v226, v125, v125
	v_fmac_f32_e32 v226, v62, v62
	v_fmac_f32_e32 v226, v63, v63
	v_fmac_f32_e32 v226, v64, v64
	v_fmac_f32_e32 v226, v65, v65
	v_fmac_f32_e32 v226, v58, v58
	v_fmac_f32_e32 v226, v59, v59
	v_fmac_f32_e32 v226, v60, v60
	v_fmac_f32_e32 v226, v61, v61
	v_mul_f32_e32 v227, v118, v118
	v_fmac_f32_e32 v227, v119, v119
	v_fmac_f32_e32 v227, v120, v120
	v_fmac_f32_e32 v227, v121, v121
	v_fmac_f32_e32 v227, v114, v114
	v_fmac_f32_e32 v227, v115, v115
	v_fmac_f32_e32 v227, v116, v116
	v_fmac_f32_e32 v227, v117, v117
	v_fmac_f32_e32 v227, v54, v54
	v_fmac_f32_e32 v227, v55, v55
	v_fmac_f32_e32 v227, v56, v56
	v_fmac_f32_e32 v227, v57, v57
	v_fmac_f32_e32 v227, v50, v50
	v_fmac_f32_e32 v227, v51, v51
	v_fmac_f32_e32 v227, v52, v52
	v_fmac_f32_e32 v227, v53, v53
	v_mul_f32_e32 v228, v110, v110
	v_fmac_f32_e32 v228, v111, v111
	v_fmac_f32_e32 v228, v112, v112
	v_fmac_f32_e32 v228, v113, v113
	v_fmac_f32_e32 v228, v106, v106
	v_fmac_f32_e32 v228, v107, v107
	v_fmac_f32_e32 v228, v108, v108
	v_fmac_f32_e32 v228, v109, v109
	v_fmac_f32_e32 v228, v46, v46
	v_fmac_f32_e32 v228, v47, v47
	v_fmac_f32_e32 v228, v48, v48
	v_fmac_f32_e32 v228, v49, v49
	v_fmac_f32_e32 v228, v42, v42
	v_fmac_f32_e32 v228, v43, v43
	v_fmac_f32_e32 v228, v44, v44
	v_fmac_f32_e32 v228, v45, v45
	v_mul_f32_e32 v229, v102, v102
	v_fmac_f32_e32 v229, v103, v103
	v_fmac_f32_e32 v229, v104, v104
	v_fmac_f32_e32 v229, v105, v105
	v_fmac_f32_e32 v229, v98, v98
	v_fmac_f32_e32 v229, v99, v99
	v_fmac_f32_e32 v229, v100, v100
	v_fmac_f32_e32 v229, v101, v101
	v_fmac_f32_e32 v229, v38, v38
	v_fmac_f32_e32 v229, v39, v39
	v_fmac_f32_e32 v229, v40, v40
	v_fmac_f32_e32 v229, v41, v41
	v_fmac_f32_e32 v229, v34, v34
	v_fmac_f32_e32 v229, v35, v35
	v_fmac_f32_e32 v229, v36, v36
	v_fmac_f32_e32 v229, v37, v37
	v_mul_f32_e32 v230, v94, v94
	v_fmac_f32_e32 v230, v95, v95
	v_fmac_f32_e32 v230, v96, v96
	v_fmac_f32_e32 v230, v97, v97
	v_fmac_f32_e32 v230, v90, v90
	v_fmac_f32_e32 v230, v91, v91
	v_fmac_f32_e32 v230, v92, v92
	v_fmac_f32_e32 v230, v93, v93
	v_fmac_f32_e32 v230, v30, v30
	v_fmac_f32_e32 v230, v31, v31
	v_fmac_f32_e32 v230, v32, v32
	v_fmac_f32_e32 v230, v33, v33
	v_fmac_f32_e32 v230, v26, v26
	v_fmac_f32_e32 v230, v27, v27
	v_fmac_f32_e32 v230, v28, v28
	v_fmac_f32_e32 v230, v29, v29
	v_mul_f32_e32 v231, v86, v86
	v_fmac_f32_e32 v231, v87, v87
	v_fmac_f32_e32 v231, v88, v88
	v_fmac_f32_e32 v231, v89, v89
	v_fmac_f32_e32 v231, v82, v82
	v_fmac_f32_e32 v231, v83, v83
	v_fmac_f32_e32 v231, v84, v84
	v_fmac_f32_e32 v231, v85, v85
	v_fmac_f32_e32 v231, v22, v22
	v_fmac_f32_e32 v231, v23, v23
	v_fmac_f32_e32 v231, v24, v24
	v_fmac_f32_e32 v231, v25, v25
	v_fmac_f32_e32 v231, v18, v18
	v_fmac_f32_e32 v231, v19, v19
	v_fmac_f32_e32 v231, v20, v20
	v_fmac_f32_e32 v231, v21, v21
	v_mul_f32_e32 v232, v78, v78
	v_fmac_f32_e32 v232, v79, v79
	v_fmac_f32_e32 v232, v80, v80
	v_fmac_f32_e32 v232, v81, v81
	v_fmac_f32_e32 v232, v74, v74
	v_fmac_f32_e32 v232, v75, v75
	v_fmac_f32_e32 v232, v76, v76
	v_fmac_f32_e32 v232, v77, v77
	v_fmac_f32_e32 v232, v14, v14
	v_fmac_f32_e32 v232, v15, v15
	v_fmac_f32_e32 v232, v16, v16
	v_fmac_f32_e32 v232, v17, v17
	v_fmac_f32_e32 v232, v10, v10
	v_fmac_f32_e32 v232, v11, v11
	v_fmac_f32_e32 v232, v12, v12
	v_fmac_f32_e32 v232, v13, v13
	v_mul_f32_e32 v233, v70, v70
	v_fmac_f32_e32 v233, v71, v71
	v_fmac_f32_e32 v233, v72, v72
	v_fmac_f32_e32 v233, v73, v73
	v_fmac_f32_e32 v233, v66, v66
	v_fmac_f32_e32 v233, v67, v67
	v_fmac_f32_e32 v233, v68, v68
	v_fmac_f32_e32 v233, v69, v69
	v_fmac_f32_e32 v233, v6, v6
	v_fmac_f32_e32 v233, v7, v7
	v_fmac_f32_e32 v233, v8, v8
	v_fmac_f32_e32 v233, v9, v9
	v_fmac_f32_e32 v233, v2, v2
	v_fmac_f32_e32 v233, v3, v3
	v_fmac_f32_e32 v233, v4, v4
	v_fmac_f32_e32 v233, v5, v5
	v_mov_b32_e32 v234, v226
	v_mov_b32_e32 v235, v227
	v_mov_b32_e32 v236, v228
	v_mov_b32_e32 v237, v229
	v_mov_b32_e32 v242, v230
	v_mov_b32_e32 v243, v231
	v_mov_b32_e32 v244, v232
	v_mov_b32_e32 v245, v233
	v_permlane32_swap_b32_e32 v226, v234
	v_permlane32_swap_b32_e32 v227, v235
	v_permlane32_swap_b32_e32 v228, v236
	v_permlane32_swap_b32_e32 v229, v237
	v_permlane32_swap_b32_e32 v230, v242
	v_permlane32_swap_b32_e32 v231, v243
	v_permlane32_swap_b32_e32 v232, v244
	v_permlane32_swap_b32_e32 v233, v245
	v_add_f32_e32 v226, v226, v234
	v_add_f32_e32 v227, v227, v235
	v_add_f32_e32 v228, v228, v236
	v_add_f32_e32 v229, v229, v237
	v_add_f32_e32 v230, v230, v242
	v_add_f32_e32 v231, v231, v243
	v_add_f32_e32 v232, v232, v244
	v_add_f32_e32 v233, v233, v245
	v_mov_b32_e32 v234, v226
	v_mov_b32_e32 v235, v227
	v_mov_b32_e32 v236, v228
	v_mov_b32_e32 v237, v229
	v_mov_b32_e32 v242, v230
	v_mov_b32_e32 v243, v231
	v_mov_b32_e32 v244, v232
	v_mov_b32_e32 v245, v233
	v_permlane16_swap_b32_e32 v226, v234
	v_permlane16_swap_b32_e32 v227, v235
	v_permlane16_swap_b32_e32 v228, v236
	v_permlane16_swap_b32_e32 v229, v237
	v_permlane16_swap_b32_e32 v230, v242
	v_permlane16_swap_b32_e32 v231, v243
	v_permlane16_swap_b32_e32 v232, v244
	v_permlane16_swap_b32_e32 v233, v245
	v_add_f32_e32 v226, v226, v234
	v_add_f32_e32 v227, v227, v235
	v_add_f32_e32 v228, v228, v236
	v_add_f32_e32 v229, v229, v237
	v_add_f32_e32 v230, v230, v242
	v_add_f32_e32 v231, v231, v243
	v_add_f32_e32 v232, v232, v244
	v_add_f32_e32 v233, v233, v245
	s_lshr_b32 s2, s49, 6
	s_and_b32 s3, s2, 3
	s_lshr_b32 s2, s2, 2
	s_lshl_b32 s2, s2, 10
	s_lshl_b32 s3, s3, 2
	s_add_i32 s2, s2, s3
	s_add_i32 s2, s2, 0x21400
	v_and_b32_e32 v181, 15, v202
	v_lshl_add_u32 v181, v181, 4, s2
	s_mov_b64 s[34:35], exec
	s_mov_b64 exec, 0xffff
	ds_write_b32 v181, v226
	ds_write_b32 v181, v227 offset:256
	ds_write_b32 v181, v228 offset:512
	ds_write_b32 v181, v229 offset:768
	ds_write_b32 v181, v230 offset:2048
	ds_write_b32 v181, v231 offset:2304
	ds_write_b32 v181, v232 offset:2560
	ds_write_b32 v181, v233 offset:2816
	s_mov_b64 exec, s[34:35]
	s_waitcnt vmcnt(0) lgkmcnt(0)
	s_barrier
	v_add_f32_e32 v146, 1.0, v146
	v_add_f32_e32 v147, 1.0, v147
	v_add_f32_e32 v148, 1.0, v148
	v_add_f32_e32 v149, 1.0, v149
	v_add_f32_e32 v150, 1.0, v150
	v_add_f32_e32 v151, 1.0, v151
	v_add_f32_e32 v152, 1.0, v152
	v_add_f32_e32 v153, 1.0, v153
	v_add_f32_e32 v154, 1.0, v154
	v_add_f32_e32 v155, 1.0, v155
	v_add_f32_e32 v156, 1.0, v156
	v_add_f32_e32 v157, 1.0, v157
	v_add_f32_e32 v158, 1.0, v158
	v_add_f32_e32 v159, 1.0, v159
	v_add_f32_e32 v160, 1.0, v160
	v_add_f32_e32 v161, 1.0, v161
	v_mul_f32_e32 v130, v130, v146
	v_mul_f32_e32 v131, v131, v147
	v_mul_f32_e32 v132, v132, v148
	v_mul_f32_e32 v133, v133, v149
	v_mul_f32_e32 v134, v134, v150
	v_mul_f32_e32 v135, v135, v151
	v_mul_f32_e32 v136, v136, v152
	v_mul_f32_e32 v137, v137, v153
	v_mul_f32_e32 v138, v138, v154
	v_mul_f32_e32 v139, v139, v155
	v_mul_f32_e32 v140, v140, v156
	v_mul_f32_e32 v141, v141, v157
	v_mul_f32_e32 v142, v142, v158
	v_mul_f32_e32 v143, v143, v159
	v_mul_f32_e32 v144, v144, v160
	v_mul_f32_e32 v145, v145, v161
	s_lshl_b32 s2, s86, 12
	s_add_u32 s2, s8, s2
	s_addc_u32 s3, s9, 0
	s_add_u32 s2, s2, 0x15234000
	s_addc_u32 s3, s3, 0
	s_lshl_b32 s12, s87, 10
	s_add_u32 s12, s2, s12
	s_addc_u32 s13, s3, 0
	s_lshl_b32 s42, s86, 5
	s_add_u32 s42, s8, s42
	s_addc_u32 s43, s9, 0
	s_add_u32 s42, s42, 0x3600
	s_addc_u32 s43, s43, 0
	s_cmpk_gt_u32 s49, 0xff
	s_cbranch_scc1 .Lfz_p1
	s_movk_i32 s44, 0x1400
	s_add_i32 s44, s44, 0x20000
	v_lshl_add_u32 v154, v202, 4, s44
	v_lshlrev_b32_e32 v155, 2, v202
	ds_read_b128 v[146:149], v154
	s_waitcnt lgkmcnt(0)
	v_add_f32_e32 v146, v146, v147
	v_add_f32_e32 v148, v148, v149
	v_add_f32_e32 v146, v146, v148
	global_store_dword v155, v146, s[12:13] sc0 sc1
.Lfz_p1:
	s_waitcnt vmcnt(0)
	s_barrier
	s_cmpk_lt_u32 s49, 64
	s_cbranch_scc0 .Lfz_arr
	s_mov_b64 s[34:35], exec
	s_mov_b64 exec, 1
	v_mov_b32_e32 v158, 0
	v_mov_b32_e32 v159, 1
	global_atomic_add v158, v159, s[42:43]
	s_mov_b32 s44, 0
.Lfz_poll:
	global_load_dword v159, v158, s[42:43] sc1
	s_waitcnt vmcnt(0)
	v_readfirstlane_b32 s45, v159
	s_cmp_ge_u32 s45, s88
	s_cbranch_scc1 .Lfz_polled
	s_add_i32 s44, s44, 1
	s_cmp_lt_u32 s44, 0x4000
	s_cbranch_scc0 .Lfz_polled
	s_sleep 1
	s_branch .Lfz_poll
.Lfz_polled:
	s_mov_b64 exec, s[34:35]
.Lfz_arr:
	s_barrier
	s_cmpk_gt_u32 s49, 0xff
	s_cbranch_scc1 .Lfz_p2
	global_load_dword v146, v155, s[2:3] sc0 sc1
	global_load_dword v147, v155, s[2:3] offset:1024 sc0 sc1
	global_load_dword v148, v155, s[2:3] offset:2048 sc0 sc1
	global_load_dword v149, v155, s[2:3] offset:3072 sc0 sc1
	v_mov_b32_e32 v150, 0x3a800000
	s_movk_i32 s44, 0x2400
	s_add_i32 s44, s44, 0x20000
	v_add_u32_e32 v151, s44, v155
	s_waitcnt vmcnt(0)
	v_add_f32_e32 v146, v146, v147
	v_add_f32_e32 v148, v148, v149
	v_add_f32_e32 v146, v146, v148
	v_fma_f32 v146, v146, v150, v203
	v_rsq_f32_e32 v146, v146
	s_nop 0
	ds_write_b32 v151, v146
	s_waitcnt lgkmcnt(0)
.Lfz_p2:
	s_barrier
	s_lshr_b32 s2, s49, 8
	s_lshl_b32 s3, s2, 8
	s_movk_i32 s44, 0x2400
	s_add_i32 s44, s44, 0x20000
	s_add_i32 s3, s3, s44
	v_and_b32_e32 v156, 15, v202
	v_lshl_add_u32 v156, v156, 2, s3
	ds_read_b32 v162, v156
	ds_read_b32 v163, v156 offset:64
	ds_read_b32 v164, v156 offset:128
	ds_read_b32 v165, v156 offset:192
	ds_read_b32 v166, v156 offset:512
	ds_read_b32 v167, v156 offset:576
	ds_read_b32 v168, v156 offset:640
	ds_read_b32 v169, v156 offset:704
	v_and_b32_e32 v157, 15, v202
	v_lshlrev_b32_e32 v157, 11, v157
	v_lshl_or_b32 v157, v179, 3, v157
	v_readlane_b32 s44, v252, 20
	v_readlane_b32 s45, v252, 21
	s_lshl_b32 s3, s86, 8
	s_lshl_b32 s2, s2, 6
	s_add_i32 s3, s3, s2
	s_add_i32 s3, s3, 1
	s_lshl_b32 s3, s3, 11
	s_lshr_b32 s2, s49, 6
	s_and_b32 s2, s2, 3
	s_lshl_b32 s2, s2, 6
	s_lshl_b32 s12, s87, 9
	s_add_i32 s2, s2, s12
	s_add_i32 s3, s3, s2
	s_add_u32 s44, s44, s3
	s_addc_u32 s45, s45, 0
	s_waitcnt lgkmcnt(0)
	v_mul_f32_e32 v146, v162, v126
	v_mul_f32_e32 v147, v162, v127
	v_mul_f32_e32 v148, v162, v128
	v_mul_f32_e32 v149, v162, v129
	v_fma_f32 v146, v146, v130, v186
	v_fma_f32 v147, v147, v131, v187
	v_fma_f32 v148, v148, v132, v188
	v_fma_f32 v149, v149, v133, v189
	v_cvt_pk_bf16_f32 v150, v146, v147
	v_cvt_pk_bf16_f32 v151, v148, v149
	global_store_dwordx2 v157, v[150:151], s[44:45]
	v_mul_f32_e32 v146, v162, v122
	v_mul_f32_e32 v147, v162, v123
	v_mul_f32_e32 v148, v162, v124
	v_mul_f32_e32 v149, v162, v125
	v_fma_f32 v146, v146, v134, v190
	v_fma_f32 v147, v147, v135, v191
	v_fma_f32 v148, v148, v136, v192
	v_fma_f32 v149, v149, v137, v193
	v_cvt_pk_bf16_f32 v152, v146, v147
	v_cvt_pk_bf16_f32 v153, v148, v149
	global_store_dwordx2 v157, v[152:153], s[44:45] offset:32
	v_mul_f32_e32 v146, v162, v62
	v_mul_f32_e32 v147, v162, v63
	v_mul_f32_e32 v148, v162, v64
	v_mul_f32_e32 v149, v162, v65
	v_fma_f32 v146, v146, v138, v194
	v_fma_f32 v147, v147, v139, v195
	v_fma_f32 v148, v148, v140, v196
	v_fma_f32 v149, v149, v141, v197
	v_cvt_pk_bf16_f32 v154, v146, v147
	v_cvt_pk_bf16_f32 v155, v148, v149
	global_store_dwordx2 v157, v[154:155], s[44:45] offset:256
	v_mul_f32_e32 v146, v162, v58
	v_mul_f32_e32 v147, v162, v59
	v_mul_f32_e32 v148, v162, v60
	v_mul_f32_e32 v149, v162, v61
	v_fma_f32 v146, v146, v142, v198
	v_fma_f32 v147, v147, v143, v199
	v_fma_f32 v148, v148, v144, v200
	v_fma_f32 v149, v149, v145, v201
	v_cvt_pk_bf16_f32 v158, v146, v147
	v_cvt_pk_bf16_f32 v159, v148, v149
	global_store_dwordx2 v157, v[158:159], s[44:45] offset:288
	s_add_u32 s44, s44, 0x8000
	s_addc_u32 s45, s45, 0
	v_mul_f32_e32 v146, v163, v118
	v_mul_f32_e32 v147, v163, v119
	v_mul_f32_e32 v148, v163, v120
	v_mul_f32_e32 v149, v163, v121
	v_fma_f32 v146, v146, v130, v186
	v_fma_f32 v147, v147, v131, v187
	v_fma_f32 v148, v148, v132, v188
	v_fma_f32 v149, v149, v133, v189
	v_cvt_pk_bf16_f32 v150, v146, v147
	v_cvt_pk_bf16_f32 v151, v148, v149
	global_store_dwordx2 v157, v[150:151], s[44:45]
	v_mul_f32_e32 v146, v163, v114
	v_mul_f32_e32 v147, v163, v115
	v_mul_f32_e32 v148, v163, v116
	v_mul_f32_e32 v149, v163, v117
	v_fma_f32 v146, v146, v134, v190
	v_fma_f32 v147, v147, v135, v191
	v_fma_f32 v148, v148, v136, v192
	v_fma_f32 v149, v149, v137, v193
	v_cvt_pk_bf16_f32 v152, v146, v147
	v_cvt_pk_bf16_f32 v153, v148, v149
	global_store_dwordx2 v157, v[152:153], s[44:45] offset:32
	v_mul_f32_e32 v146, v163, v54
	v_mul_f32_e32 v147, v163, v55
	v_mul_f32_e32 v148, v163, v56
	v_mul_f32_e32 v149, v163, v57
	v_fma_f32 v146, v146, v138, v194
	v_fma_f32 v147, v147, v139, v195
	v_fma_f32 v148, v148, v140, v196
	v_fma_f32 v149, v149, v141, v197
	v_cvt_pk_bf16_f32 v154, v146, v147
	v_cvt_pk_bf16_f32 v155, v148, v149
	global_store_dwordx2 v157, v[154:155], s[44:45] offset:256
	v_mul_f32_e32 v146, v163, v50
	v_mul_f32_e32 v147, v163, v51
	v_mul_f32_e32 v148, v163, v52
	v_mul_f32_e32 v149, v163, v53
	v_fma_f32 v146, v146, v142, v198
	v_fma_f32 v147, v147, v143, v199
	v_fma_f32 v148, v148, v144, v200
	v_fma_f32 v149, v149, v145, v201
	v_cvt_pk_bf16_f32 v158, v146, v147
	v_cvt_pk_bf16_f32 v159, v148, v149
	global_store_dwordx2 v157, v[158:159], s[44:45] offset:288
	s_add_u32 s44, s44, 0x8000
	s_addc_u32 s45, s45, 0
	v_mul_f32_e32 v146, v164, v110
	v_mul_f32_e32 v147, v164, v111
	v_mul_f32_e32 v148, v164, v112
	v_mul_f32_e32 v149, v164, v113
	v_fma_f32 v146, v146, v130, v186
	v_fma_f32 v147, v147, v131, v187
	v_fma_f32 v148, v148, v132, v188
	v_fma_f32 v149, v149, v133, v189
	v_cvt_pk_bf16_f32 v150, v146, v147
	v_cvt_pk_bf16_f32 v151, v148, v149
	global_store_dwordx2 v157, v[150:151], s[44:45]
	v_mul_f32_e32 v146, v164, v106
	v_mul_f32_e32 v147, v164, v107
	v_mul_f32_e32 v148, v164, v108
	v_mul_f32_e32 v149, v164, v109
	v_fma_f32 v146, v146, v134, v190
	v_fma_f32 v147, v147, v135, v191
	v_fma_f32 v148, v148, v136, v192
	v_fma_f32 v149, v149, v137, v193
	v_cvt_pk_bf16_f32 v152, v146, v147
	v_cvt_pk_bf16_f32 v153, v148, v149
	global_store_dwordx2 v157, v[152:153], s[44:45] offset:32
	v_mul_f32_e32 v146, v164, v46
	v_mul_f32_e32 v147, v164, v47
	v_mul_f32_e32 v148, v164, v48
	v_mul_f32_e32 v149, v164, v49
	v_fma_f32 v146, v146, v138, v194
	v_fma_f32 v147, v147, v139, v195
	v_fma_f32 v148, v148, v140, v196
	v_fma_f32 v149, v149, v141, v197
	v_cvt_pk_bf16_f32 v154, v146, v147
	v_cvt_pk_bf16_f32 v155, v148, v149
	global_store_dwordx2 v157, v[154:155], s[44:45] offset:256
	v_mul_f32_e32 v146, v164, v42
	v_mul_f32_e32 v147, v164, v43
	v_mul_f32_e32 v148, v164, v44
	v_mul_f32_e32 v149, v164, v45
	v_fma_f32 v146, v146, v142, v198
	v_fma_f32 v147, v147, v143, v199
	v_fma_f32 v148, v148, v144, v200
	v_fma_f32 v149, v149, v145, v201
	v_cvt_pk_bf16_f32 v158, v146, v147
	v_cvt_pk_bf16_f32 v159, v148, v149
	global_store_dwordx2 v157, v[158:159], s[44:45] offset:288
	s_add_u32 s44, s44, 0x8000
	s_addc_u32 s45, s45, 0
	v_mul_f32_e32 v146, v165, v102
	v_mul_f32_e32 v147, v165, v103
	v_mul_f32_e32 v148, v165, v104
	v_mul_f32_e32 v149, v165, v105
	v_fma_f32 v146, v146, v130, v186
	v_fma_f32 v147, v147, v131, v187
	v_fma_f32 v148, v148, v132, v188
	v_fma_f32 v149, v149, v133, v189
	v_cvt_pk_bf16_f32 v150, v146, v147
	v_cvt_pk_bf16_f32 v151, v148, v149
	global_store_dwordx2 v157, v[150:151], s[44:45]
	v_mul_f32_e32 v146, v165, v98
	v_mul_f32_e32 v147, v165, v99
	v_mul_f32_e32 v148, v165, v100
	v_mul_f32_e32 v149, v165, v101
	v_fma_f32 v146, v146, v134, v190
	v_fma_f32 v147, v147, v135, v191
	v_fma_f32 v148, v148, v136, v192
	v_fma_f32 v149, v149, v137, v193
	v_cvt_pk_bf16_f32 v152, v146, v147
	v_cvt_pk_bf16_f32 v153, v148, v149
	global_store_dwordx2 v157, v[152:153], s[44:45] offset:32
	v_mul_f32_e32 v146, v165, v38
	v_mul_f32_e32 v147, v165, v39
	v_mul_f32_e32 v148, v165, v40
	v_mul_f32_e32 v149, v165, v41
	v_fma_f32 v146, v146, v138, v194
	v_fma_f32 v147, v147, v139, v195
	v_fma_f32 v148, v148, v140, v196
	v_fma_f32 v149, v149, v141, v197
	v_cvt_pk_bf16_f32 v154, v146, v147
	v_cvt_pk_bf16_f32 v155, v148, v149
	global_store_dwordx2 v157, v[154:155], s[44:45] offset:256
	v_mul_f32_e32 v146, v165, v34
	v_mul_f32_e32 v147, v165, v35
	v_mul_f32_e32 v148, v165, v36
	v_mul_f32_e32 v149, v165, v37
	v_fma_f32 v146, v146, v142, v198
	v_fma_f32 v147, v147, v143, v199
	v_fma_f32 v148, v148, v144, v200
	v_fma_f32 v149, v149, v145, v201
	v_cvt_pk_bf16_f32 v158, v146, v147
	v_cvt_pk_bf16_f32 v159, v148, v149
	global_store_dwordx2 v157, v[158:159], s[44:45] offset:288
	s_add_u32 s44, s44, 0x28000
	s_addc_u32 s45, s45, 0
	v_mul_f32_e32 v146, v166, v94
	v_mul_f32_e32 v147, v166, v95
	v_mul_f32_e32 v148, v166, v96
	v_mul_f32_e32 v149, v166, v97
	v_fma_f32 v146, v146, v130, v186
	v_fma_f32 v147, v147, v131, v187
	v_fma_f32 v148, v148, v132, v188
	v_fma_f32 v149, v149, v133, v189
	v_cvt_pk_bf16_f32 v150, v146, v147
	v_cvt_pk_bf16_f32 v151, v148, v149
	global_store_dwordx2 v157, v[150:151], s[44:45]
	v_mul_f32_e32 v146, v166, v90
	v_mul_f32_e32 v147, v166, v91
	v_mul_f32_e32 v148, v166, v92
	v_mul_f32_e32 v149, v166, v93
	v_fma_f32 v146, v146, v134, v190
	v_fma_f32 v147, v147, v135, v191
	v_fma_f32 v148, v148, v136, v192
	v_fma_f32 v149, v149, v137, v193
	v_cvt_pk_bf16_f32 v152, v146, v147
	v_cvt_pk_bf16_f32 v153, v148, v149
	global_store_dwordx2 v157, v[152:153], s[44:45] offset:32
	v_mul_f32_e32 v146, v166, v30
	v_mul_f32_e32 v147, v166, v31
	v_mul_f32_e32 v148, v166, v32
	v_mul_f32_e32 v149, v166, v33
	v_fma_f32 v146, v146, v138, v194
	v_fma_f32 v147, v147, v139, v195
	v_fma_f32 v148, v148, v140, v196
	v_fma_f32 v149, v149, v141, v197
	v_cvt_pk_bf16_f32 v154, v146, v147
	v_cvt_pk_bf16_f32 v155, v148, v149
	global_store_dwordx2 v157, v[154:155], s[44:45] offset:256
	v_mul_f32_e32 v146, v166, v26
	v_mul_f32_e32 v147, v166, v27
	v_mul_f32_e32 v148, v166, v28
	v_mul_f32_e32 v149, v166, v29
	v_fma_f32 v146, v146, v142, v198
	v_fma_f32 v147, v147, v143, v199
	v_fma_f32 v148, v148, v144, v200
	v_fma_f32 v149, v149, v145, v201
	v_cvt_pk_bf16_f32 v158, v146, v147
	v_cvt_pk_bf16_f32 v159, v148, v149
	global_store_dwordx2 v157, v[158:159], s[44:45] offset:288
	s_add_u32 s44, s44, 0x8000
	s_addc_u32 s45, s45, 0
	v_mul_f32_e32 v146, v167, v86
	v_mul_f32_e32 v147, v167, v87
	v_mul_f32_e32 v148, v167, v88
	v_mul_f32_e32 v149, v167, v89
	v_fma_f32 v146, v146, v130, v186
	v_fma_f32 v147, v147, v131, v187
	v_fma_f32 v148, v148, v132, v188
	v_fma_f32 v149, v149, v133, v189
	v_cvt_pk_bf16_f32 v150, v146, v147
	v_cvt_pk_bf16_f32 v151, v148, v149
	global_store_dwordx2 v157, v[150:151], s[44:45]
	v_mul_f32_e32 v146, v167, v82
	v_mul_f32_e32 v147, v167, v83
	v_mul_f32_e32 v148, v167, v84
	v_mul_f32_e32 v149, v167, v85
	v_fma_f32 v146, v146, v134, v190
	v_fma_f32 v147, v147, v135, v191
	v_fma_f32 v148, v148, v136, v192
	v_fma_f32 v149, v149, v137, v193
	v_cvt_pk_bf16_f32 v152, v146, v147
	v_cvt_pk_bf16_f32 v153, v148, v149
	global_store_dwordx2 v157, v[152:153], s[44:45] offset:32
	v_mul_f32_e32 v146, v167, v22
	v_mul_f32_e32 v147, v167, v23
	v_mul_f32_e32 v148, v167, v24
	v_mul_f32_e32 v149, v167, v25
	v_fma_f32 v146, v146, v138, v194
	v_fma_f32 v147, v147, v139, v195
	v_fma_f32 v148, v148, v140, v196
	v_fma_f32 v149, v149, v141, v197
	v_cvt_pk_bf16_f32 v154, v146, v147
	v_cvt_pk_bf16_f32 v155, v148, v149
	global_store_dwordx2 v157, v[154:155], s[44:45] offset:256
	v_mul_f32_e32 v146, v167, v18
	v_mul_f32_e32 v147, v167, v19
	v_mul_f32_e32 v148, v167, v20
	v_mul_f32_e32 v149, v167, v21
	v_fma_f32 v146, v146, v142, v198
	v_fma_f32 v147, v147, v143, v199
	v_fma_f32 v148, v148, v144, v200
	v_fma_f32 v149, v149, v145, v201
	v_cvt_pk_bf16_f32 v158, v146, v147
	v_cvt_pk_bf16_f32 v159, v148, v149
	global_store_dwordx2 v157, v[158:159], s[44:45] offset:288
	s_add_u32 s44, s44, 0x8000
	s_addc_u32 s45, s45, 0
	v_mul_f32_e32 v146, v168, v78
	v_mul_f32_e32 v147, v168, v79
	v_mul_f32_e32 v148, v168, v80
	v_mul_f32_e32 v149, v168, v81
	v_fma_f32 v146, v146, v130, v186
	v_fma_f32 v147, v147, v131, v187
	v_fma_f32 v148, v148, v132, v188
	v_fma_f32 v149, v149, v133, v189
	v_cvt_pk_bf16_f32 v150, v146, v147
	v_cvt_pk_bf16_f32 v151, v148, v149
	global_store_dwordx2 v157, v[150:151], s[44:45]
	v_mul_f32_e32 v146, v168, v74
	v_mul_f32_e32 v147, v168, v75
	v_mul_f32_e32 v148, v168, v76
	v_mul_f32_e32 v149, v168, v77
	v_fma_f32 v146, v146, v134, v190
	v_fma_f32 v147, v147, v135, v191
	v_fma_f32 v148, v148, v136, v192
	v_fma_f32 v149, v149, v137, v193
	v_cvt_pk_bf16_f32 v152, v146, v147
	v_cvt_pk_bf16_f32 v153, v148, v149
	global_store_dwordx2 v157, v[152:153], s[44:45] offset:32
	v_mul_f32_e32 v146, v168, v14
	v_mul_f32_e32 v147, v168, v15
	v_mul_f32_e32 v148, v168, v16
	v_mul_f32_e32 v149, v168, v17
	v_fma_f32 v146, v146, v138, v194
	v_fma_f32 v147, v147, v139, v195
	v_fma_f32 v148, v148, v140, v196
	v_fma_f32 v149, v149, v141, v197
	v_cvt_pk_bf16_f32 v154, v146, v147
	v_cvt_pk_bf16_f32 v155, v148, v149
	global_store_dwordx2 v157, v[154:155], s[44:45] offset:256
	v_mul_f32_e32 v146, v168, v10
	v_mul_f32_e32 v147, v168, v11
	v_mul_f32_e32 v148, v168, v12
	v_mul_f32_e32 v149, v168, v13
	v_fma_f32 v146, v146, v142, v198
	v_fma_f32 v147, v147, v143, v199
	v_fma_f32 v148, v148, v144, v200
	v_fma_f32 v149, v149, v145, v201
	v_cvt_pk_bf16_f32 v158, v146, v147
	v_cvt_pk_bf16_f32 v159, v148, v149
	global_store_dwordx2 v157, v[158:159], s[44:45] offset:288
	s_add_u32 s44, s44, 0x8000
	s_addc_u32 s45, s45, 0
	v_mul_f32_e32 v146, v169, v70
	v_mul_f32_e32 v147, v169, v71
	v_mul_f32_e32 v148, v169, v72
	v_mul_f32_e32 v149, v169, v73
	v_fma_f32 v146, v146, v130, v186
	v_fma_f32 v147, v147, v131, v187
	v_fma_f32 v148, v148, v132, v188
	v_fma_f32 v149, v149, v133, v189
	v_cvt_pk_bf16_f32 v150, v146, v147
	v_cvt_pk_bf16_f32 v151, v148, v149
	global_store_dwordx2 v157, v[150:151], s[44:45]
	v_mul_f32_e32 v146, v169, v66
	v_mul_f32_e32 v147, v169, v67
	v_mul_f32_e32 v148, v169, v68
	v_mul_f32_e32 v149, v169, v69
	v_fma_f32 v146, v146, v134, v190
	v_fma_f32 v147, v147, v135, v191
	v_fma_f32 v148, v148, v136, v192
	v_fma_f32 v149, v149, v137, v193
	v_cvt_pk_bf16_f32 v152, v146, v147
	v_cvt_pk_bf16_f32 v153, v148, v149
	global_store_dwordx2 v157, v[152:153], s[44:45] offset:32
	v_mul_f32_e32 v146, v169, v6
	v_mul_f32_e32 v147, v169, v7
	v_mul_f32_e32 v148, v169, v8
	v_mul_f32_e32 v149, v169, v9
	v_fma_f32 v146, v146, v138, v194
	v_fma_f32 v147, v147, v139, v195
	v_fma_f32 v148, v148, v140, v196
	v_fma_f32 v149, v149, v141, v197
	v_cvt_pk_bf16_f32 v154, v146, v147
	v_cvt_pk_bf16_f32 v155, v148, v149
	global_store_dwordx2 v157, v[154:155], s[44:45] offset:256
	v_mul_f32_e32 v146, v169, v2
	v_mul_f32_e32 v147, v169, v3
	v_mul_f32_e32 v148, v169, v4
	v_mul_f32_e32 v149, v169, v5
	v_fma_f32 v146, v146, v142, v198
	v_fma_f32 v147, v147, v143, v199
	v_fma_f32 v148, v148, v144, v200
	v_fma_f32 v149, v149, v145, v201
	v_cvt_pk_bf16_f32 v158, v146, v147
	v_cvt_pk_bf16_f32 v159, v148, v149
	global_store_dwordx2 v157, v[158:159], s[44:45] offset:288
	s_cmpk_gt_u32 s49, 0xff
	s_cbranch_scc0 .Lfz_skip
	s_barrier
.Lfz_skip:
	s_branch .LBB0_163
.LBB0_191:
	s_setprio 0
	s_waitcnt vmcnt(0)
	s_cmpk_gt_u32 s49, 0xff
	s_cbranch_scc1 .LBB0_193
	s_barrier

.LBB0_525:
	s_nop 0
	v_readlane_b32 s0, v255, 15
	v_readlane_b32 s1, v255, 16
	s_and_b64 vcc, exec, s[0:1]
	s_cbranch_vccz .LBB0_549
	s_mov_b64 s[16:17], s[62:63]
	v_readlane_b32 s60, v254, 42
	s_cmp_lg_u32 s97, 6
	v_readlane_b32 s61, v254, 43
	v_readlane_b32 s62, v254, 44
	v_readlane_b32 s63, v254, 45
	v_readlane_b32 s64, v254, 46
	v_readlane_b32 s65, v254, 47
	v_readlane_b32 s66, v254, 48
	v_readlane_b32 s67, v254, 49
	s_cselect_b64 s[14:15], -1, 0
	v_readlane_b32 s52, v254, 7
	s_and_b64 s[0:1], s[14:15], exec
	v_readlane_b32 s72, v254, 54
	v_readlane_b32 s73, v254, 55
	v_readlane_b32 s66, v254, 21
	v_readlane_b32 s67, v254, 22
	s_cselect_b32 s2, 0, 0x3000
	s_cselect_b32 s3, s73, s67
	s_cselect_b32 s12, s72, s66
	s_lshl_b64 s[0:1], s[16:17], 12
	s_add_u32 s0, s12, s0
	v_mov_b32_e32 v2, v202
	s_addc_u32 s1, s3, s1
	s_mul_hi_i32 s3, s16, 0xc000
	s_mul_i32 s12, s16, 0xc000
	v_readlane_b32 s16, v252, 11
	v_lshlrev_b32_e32 v0, 2, v2
	v_readlane_b32 s17, v252, 12
	s_add_u32 s12, s16, s12
	v_and_b32_e32 v3, 0xfc, v0
	s_addc_u32 s3, s17, s3
	v_lshlrev_b32_e32 v0, 2, v3
	s_add_u32 s12, s12, s2
	v_lshl_add_u64 v[82:83], s[0:1], 0, v[0:1]
	v_ashrrev_i32_e32 v7, 6, v2
	v_readlane_b32 s0, v252, 4
	s_addc_u32 s13, s3, 0
	v_or_b32_e32 v4, 0x100, v3
	v_add_u32_e32 v84, s0, v7
	s_add_i32 s0, s10, 7
	v_or_b32_e32 v5, 0x200, v3
	v_or_b32_e32 v6, 0x300, v3
	s_cmp_lt_u32 s0, 17
	s_cselect_b64 s[38:39], -1, 0
	v_cmp_gt_i32_e32 vcc, s37, v84
	v_and_b32_e32 v116, 63, v2
	v_lshlrev_b32_e32 v92, 2, v4
	v_lshlrev_b32_e32 v90, 2, v5
	v_lshlrev_b32_e32 v88, 2, v6
	v_lshlrev_b32_e32 v86, 1, v3
	v_readlane_b32 s68, v254, 50
	v_readlane_b32 s69, v254, 51
	v_readlane_b32 s70, v254, 52
	v_readlane_b32 s71, v254, 53
	v_readlane_b32 s74, v254, 56
	v_readlane_b32 s75, v254, 57
	v_readlane_b32 s53, v254, 8
	v_readlane_b32 s54, v254, 9
	v_readlane_b32 s55, v254, 10
	v_readlane_b32 s56, v254, 11
	v_readlane_b32 s57, v254, 12
	v_readlane_b32 s58, v254, 13
	v_readlane_b32 s59, v254, 14
	v_readlane_b32 s60, v254, 15
	v_readlane_b32 s61, v254, 16
	v_readlane_b32 s62, v254, 17
	v_readlane_b32 s63, v254, 18
	v_readlane_b32 s64, v254, 19
	v_readlane_b32 s65, v254, 20
	v_readlane_b32 s0, v252, 2
	v_readlane_b32 s1, v255, 12
	s_cmp_eq_u32 s0, 0x100
	s_cbranch_scc0 .Lfn_nskip
	s_cmp_eq_u32 s97, 6
	s_cbranch_scc1 .Lfn_doskip
	s_cmp_lg_u32 s1, 0
	s_cbranch_scc0 .Lfn_nskip
.Lfn_doskip:
	s_mov_b64 vcc, 0
.Lfn_nskip:
	s_and_saveexec_b64 s[16:17], vcc
	s_cbranch_execz .LBB0_535
	s_add_u32 s0, s12, 0x1000
	s_addc_u32 s1, s13, 0
	global_load_dwordx4 v[2:5], v[82:83], off
	global_load_dwordx4 v[6:9], v0, s[0:1]
	v_readlane_b32 s60, v254, 42
	v_ashrrev_i32_e32 v85, 31, v84
	v_readlane_b32 s61, v254, 43
	v_readlane_b32 s2, v252, 20
	v_mov_b32_e32 v87, v1
	v_readlane_b32 s3, v252, 21
	s_mov_b64 s[18:19], 0
	v_readlane_b32 s62, v254, 44
	v_lshl_add_u64 v[112:113], s[2:3], 0, v[86:87]
	v_readlane_b32 s63, v254, 45
	v_readlane_b32 s64, v254, 46
	v_readlane_b32 s65, v254, 47
	v_readlane_b32 s66, v254, 48
	v_readlane_b32 s67, v254, 49
	v_readlane_b32 s68, v254, 50
	v_readlane_b32 s69, v254, 51
	v_readlane_b32 s70, v254, 52
	v_readlane_b32 s71, v254, 53
	v_readlane_b32 s72, v254, 54
	v_readlane_b32 s73, v254, 55
	v_readlane_b32 s74, v254, 56
	v_readlane_b32 s75, v254, 57
	s_waitcnt vmcnt(0)
	v_pk_add_f32 v[8:9], v[8:9], 1.0 op_sel_hi:[1,0]
	v_pk_add_f32 v[6:7], v[6:7], 1.0 op_sel_hi:[1,0]
	v_pk_mul_f32 v[94:95], v[4:5], v[8:9]
	v_pk_mul_f32 v[96:97], v[2:3], v[6:7]
	global_load_dwordx4 v[2:5], v0, s[12:13]
	global_load_dwordx4 v[6:9], v[82:83], off offset:1024
	global_load_dwordx4 v[10:13], v92, s[0:1]
	s_waitcnt vmcnt(0)
	v_pk_add_f32 v[12:13], v[12:13], 1.0 op_sel_hi:[1,0]
	v_pk_add_f32 v[10:11], v[10:11], 1.0 op_sel_hi:[1,0]
	v_pk_mul_f32 v[98:99], v[8:9], v[12:13]
	v_pk_mul_f32 v[100:101], v[6:7], v[10:11]
	global_load_dwordx4 v[6:9], v0, s[12:13] offset:1024
	global_load_dwordx4 v[10:13], v[82:83], off offset:2048
	global_load_dwordx4 v[14:17], v90, s[0:1]
	s_waitcnt vmcnt(0)
	v_pk_add_f32 v[16:17], v[16:17], 1.0 op_sel_hi:[1,0]
	v_pk_add_f32 v[14:15], v[14:15], 1.0 op_sel_hi:[1,0]
	v_pk_mul_f32 v[102:103], v[12:13], v[16:17]
	v_pk_mul_f32 v[104:105], v[10:11], v[14:15]
	global_load_dwordx4 v[10:13], v0, s[12:13] offset:2048
	global_load_dwordx4 v[14:17], v[82:83], off offset:3072
	global_load_dwordx4 v[18:21], v88, s[0:1]
	s_and_b64 s[0:1], s[38:39], s[14:15]
	s_and_b64 s[0:1], s[0:1], exec
	v_readlane_b32 s0, v252, 5
	v_readlane_b32 s1, v252, 6
	s_cselect_b32 s1, s61, s1
	s_cselect_b32 s0, s60, s0
	v_lshl_add_u64 v[110:111], s[0:1], 0, v[0:1]
	s_waitcnt vmcnt(0)
	v_pk_add_f32 v[20:21], v[20:21], 1.0 op_sel_hi:[1,0]
	v_pk_add_f32 v[18:19], v[18:19], 1.0 op_sel_hi:[1,0]
	v_pk_mul_f32 v[106:107], v[16:17], v[20:21]
	v_pk_mul_f32 v[108:109], v[14:15], v[18:19]
	global_load_dwordx4 v[14:17], v0, s[12:13] offset:3072
	v_lshlrev_b64 v[18:19], 12, v[84:85]
	v_lshl_or_b32 v18, v116, 4, v18
	v_lshl_add_u64 v[18:19], s[0:1], 0, v[18:19]
	s_mov_b64 s[0:1], 0xc00
	v_lshl_add_u64 v[114:115], v[18:19], 0, s[0:1]
	v_mov_b32_e32 v85, v84
	s_branch .LBB0_529
